# four GEMM K-loop heads aligned to 64 bytes (.p2align 6, s_nop padding outside the loops)
# baseline (speedup 1.0000x reference)
;     __device__ __forceinline__ bool next(int i, Unit& u) const { if (i) return false; u.pm = pm; u.pn = pn; return true; }
; template <class Epi, class Sched, bool ALIGN_EPI = false, bool SP2 = false>
; __device__ __forceinline__ void gemm_phase(PG8_LAS unsigned char* lds, const Gemm g, const Sched& S, const Epi& E) {
;     ...
;         const bool has_next = S.next(ui + 1, nxt);
;         const char* nA = has_next ? (const char*)g.A + (size_t)nxt.pm * tstep : cA; const char* nB = has_next ? (const char*)g.Bt + (size_t)nxt.pn * tstep : cB;
;         for (int t = 0; t < nt; t += 2) {
;             const bool last = (t == nt - 2);
;             const char* a1 = cA + (size_t)(t + 1) * kstep;
;             const char* a2 = last ? nA : cA + (size_t)(t + 2) * kstep; const char* b2 = last ? nB : cB + (size_t)(t + 2) * kstep;
;             const char* a3 = a2 + kstep; const char* b3 = b2 + kstep;
;             if (last && has_next) S.a_ready(nxt);
;     ...
; #pragma unroll
;         for (int a = 0; a < 2; ++a)
; #pragma unroll
;             for (int b = 0; b < 2; ++b)
; #pragma unroll
;                 for (int m = 0; m < 4; ++m)
; #pragma unroll
;                     for (int n = 0; n < 2; ++n) acc[a][b][m][n] = (f32x4){0.f, 0.f, 0.f, 0.f};
;         cur = nxt; cA = nA; cB = nB; ++ui;
.LBB0_137:
	s_ashr_i32 s47, s46, 31
	s_lshl_b64 s[22:23], s[46:47], 20
	s_add_u32 s50, s55, s22
	s_addc_u32 s51, s58, s23
	s_and_b64 s[22:23], s[38:39], exec
	s_cselect_b32 s47, s51, s49
	s_cselect_b32 s84, s50, s48
	s_ashr_i32 s45, s44, 31
	s_lshl_b64 s[22:23], s[44:45], 20
	s_add_u32 s52, s20, s22
	s_addc_u32 s53, s59, s23
	s_and_b64 s[22:23], s[38:39], exec
	s_cselect_b32 s45, s53, s35
	s_cselect_b32 s85, s52, s34
	s_add_u32 s56, s48, 0x80080
	s_addc_u32 s57, s49, 0
	s_add_u32 s86, s34, 0x100
	v_mov_b32_e32 v2, 0
	s_addc_u32 s87, s35, 0
	s_mov_b32 s88, -2
	v_mov_b32_e32 v3, v2
	v_mov_b32_e32 v4, v2
	v_mov_b32_e32 v5, v2
	v_mov_b32_e32 v6, v2
	v_mov_b32_e32 v7, v2
	v_mov_b32_e32 v8, v2
	v_mov_b32_e32 v9, v2
	v_mov_b32_e32 v18, v2
	v_mov_b32_e32 v19, v2
	v_mov_b32_e32 v20, v2
	v_mov_b32_e32 v21, v2
	v_mov_b32_e32 v22, v2
	v_mov_b32_e32 v23, v2
	v_mov_b32_e32 v24, v2
	v_mov_b32_e32 v25, v2
	v_mov_b32_e32 v30, v2
	v_mov_b32_e32 v31, v2
	v_mov_b32_e32 v32, v2
	v_mov_b32_e32 v33, v2
	v_mov_b32_e32 v38, v2
	v_mov_b32_e32 v39, v2
	v_mov_b32_e32 v40, v2
	v_mov_b32_e32 v41, v2
	v_mov_b32_e32 v46, v2
	v_mov_b32_e32 v47, v2
	v_mov_b32_e32 v48, v2
	v_mov_b32_e32 v49, v2
	v_mov_b32_e32 v54, v2
	v_mov_b32_e32 v55, v2
	v_mov_b32_e32 v56, v2
	v_mov_b32_e32 v57, v2
	v_mov_b32_e32 v10, v2
	v_mov_b32_e32 v11, v2
	v_mov_b32_e32 v12, v2
	v_mov_b32_e32 v13, v2
	v_mov_b32_e32 v14, v2
	v_mov_b32_e32 v15, v2
	v_mov_b32_e32 v16, v2
	v_mov_b32_e32 v17, v2
	v_mov_b32_e32 v26, v2
	v_mov_b32_e32 v27, v2
	v_mov_b32_e32 v28, v2
	v_mov_b32_e32 v29, v2
	v_mov_b32_e32 v34, v2
	v_mov_b32_e32 v35, v2
	v_mov_b32_e32 v36, v2
	v_mov_b32_e32 v37, v2
	v_mov_b32_e32 v42, v2
	v_mov_b32_e32 v43, v2
	v_mov_b32_e32 v44, v2
	v_mov_b32_e32 v45, v2
	v_mov_b32_e32 v50, v2
	v_mov_b32_e32 v51, v2
	v_mov_b32_e32 v52, v2
	v_mov_b32_e32 v53, v2
	v_mov_b32_e32 v58, v2
	v_mov_b32_e32 v59, v2
	v_mov_b32_e32 v60, v2
	v_mov_b32_e32 v61, v2
	v_mov_b32_e32 v62, v2
	v_mov_b32_e32 v63, v2
	v_mov_b32_e32 v64, v2
	v_mov_b32_e32 v65, v2
	v_mov_b32_e32 v66, v2
	v_mov_b32_e32 v67, v2
	v_mov_b32_e32 v68, v2
	v_mov_b32_e32 v69, v2
	v_mov_b32_e32 v70, v2
	v_mov_b32_e32 v71, v2
	v_mov_b32_e32 v72, v2
	v_mov_b32_e32 v73, v2
	v_mov_b32_e32 v74, v2
	v_mov_b32_e32 v75, v2
	v_mov_b32_e32 v76, v2
	v_mov_b32_e32 v77, v2
	v_mov_b32_e32 v82, v2
	v_mov_b32_e32 v83, v2
	v_mov_b32_e32 v84, v2
	v_mov_b32_e32 v85, v2
	v_mov_b32_e32 v98, v2
	v_mov_b32_e32 v99, v2
	v_mov_b32_e32 v100, v2
	v_mov_b32_e32 v101, v2
	v_mov_b32_e32 v102, v2
	v_mov_b32_e32 v103, v2
	v_mov_b32_e32 v104, v2
	v_mov_b32_e32 v105, v2
	v_mov_b32_e32 v114, v2
	v_mov_b32_e32 v115, v2
	v_mov_b32_e32 v116, v2
	v_mov_b32_e32 v117, v2
	v_mov_b32_e32 v118, v2
	v_mov_b32_e32 v119, v2
	v_mov_b32_e32 v120, v2
	v_mov_b32_e32 v121, v2
	v_mov_b32_e32 v78, v2
	v_mov_b32_e32 v79, v2
	v_mov_b32_e32 v80, v2
	v_mov_b32_e32 v81, v2
	v_mov_b32_e32 v86, v2
	v_mov_b32_e32 v87, v2
	v_mov_b32_e32 v88, v2
	v_mov_b32_e32 v89, v2
	v_mov_b32_e32 v90, v2
	v_mov_b32_e32 v91, v2
	v_mov_b32_e32 v92, v2
	v_mov_b32_e32 v93, v2
	v_mov_b32_e32 v94, v2
	v_mov_b32_e32 v95, v2
	v_mov_b32_e32 v96, v2
	v_mov_b32_e32 v97, v2
	v_mov_b32_e32 v106, v2
	v_mov_b32_e32 v107, v2
	v_mov_b32_e32 v108, v2
	v_mov_b32_e32 v109, v2
	v_mov_b32_e32 v110, v2
	v_mov_b32_e32 v111, v2
	v_mov_b32_e32 v112, v2
	v_mov_b32_e32 v113, v2
	v_mov_b32_e32 v122, v2
	v_mov_b32_e32 v123, v2
	v_mov_b32_e32 v124, v2
	v_mov_b32_e32 v125, v2
	v_mov_b32_e32 v126, v2
	v_mov_b32_e32 v127, v2
	v_mov_b32_e32 v128, v2
	v_mov_b32_e32 v129, v2
	.p2align	6

;     __device__ __forceinline__ bool next(int i, Unit& u) const { if (i) return false; u.pm = pm; u.pn = pn; return true; }
; template <class Epi, class Sched, bool ALIGN_EPI = false, bool SP2 = false>
; __device__ __forceinline__ void gemm_phase(PG8_LAS unsigned char* lds, const Gemm g, const Sched& S, const Epi& E) {
;     ...
;         const bool has_next = S.next(ui + 1, nxt);
;         const char* nA = has_next ? (const char*)g.A + (size_t)nxt.pm * tstep : cA; const char* nB = has_next ? (const char*)g.Bt + (size_t)nxt.pn * tstep : cB;
;         for (int t = 0; t < nt; t += 2) {
;             const bool last = (t == nt - 2);
;             const char* a1 = cA + (size_t)(t + 1) * kstep;
;             const char* a2 = last ? nA : cA + (size_t)(t + 2) * kstep; const char* b2 = last ? nB : cB + (size_t)(t + 2) * kstep;
;             const char* a3 = a2 + kstep; const char* b3 = b2 + kstep;
;             if (last && has_next) S.a_ready(nxt);
;     ...
; #pragma unroll
;         for (int a = 0; a < 2; ++a)
; #pragma unroll
;             for (int b = 0; b < 2; ++b)
; #pragma unroll
;                 for (int m = 0; m < 4; ++m)
; #pragma unroll
;                     for (int n = 0; n < 2; ++n) acc[a][b][m][n] = (f32x4){0.f, 0.f, 0.f, 0.f};
;         cur = nxt; cA = nA; cB = nB; ++ui;
.LBB0_570:
	s_ashr_i32 s47, s46, 31
	s_lshl_b64 s[22:23], s[46:47], 20
	s_add_u32 s50, s20, s22
	s_addc_u32 s51, s55, s23
	s_and_b64 s[22:23], s[40:41], exec
	s_cselect_b32 s47, s51, s49
	s_cselect_b32 s84, s50, s48
	s_ashr_i32 s45, s44, 31
	s_lshl_b64 s[22:23], s[44:45], 20
	s_add_u32 s52, s58, s22
	s_addc_u32 s53, s59, s23
	s_and_b64 s[22:23], s[40:41], exec
	s_cselect_b32 s45, s53, s35
	s_cselect_b32 s85, s52, s34
	s_add_u32 s56, s48, 0x80080
	s_addc_u32 s57, s49, 0
	s_add_u32 s86, s34, 0x100
	v_mov_b32_e32 v2, 0
	s_addc_u32 s87, s35, 0
	s_mov_b32 s88, -2
	v_mov_b32_e32 v3, v2
	v_mov_b32_e32 v4, v2
	v_mov_b32_e32 v5, v2
	v_mov_b32_e32 v6, v2
	v_mov_b32_e32 v7, v2
	v_mov_b32_e32 v8, v2
	v_mov_b32_e32 v9, v2
	v_mov_b32_e32 v10, v2
	v_mov_b32_e32 v11, v2
	v_mov_b32_e32 v12, v2
	v_mov_b32_e32 v13, v2
	v_mov_b32_e32 v14, v2
	v_mov_b32_e32 v15, v2
	v_mov_b32_e32 v16, v2
	v_mov_b32_e32 v17, v2
	v_mov_b32_e32 v26, v2
	v_mov_b32_e32 v27, v2
	v_mov_b32_e32 v28, v2
	v_mov_b32_e32 v29, v2
	v_mov_b32_e32 v30, v2
	v_mov_b32_e32 v31, v2
	v_mov_b32_e32 v32, v2
	v_mov_b32_e32 v33, v2
	v_mov_b32_e32 v42, v2
	v_mov_b32_e32 v43, v2
	v_mov_b32_e32 v44, v2
	v_mov_b32_e32 v45, v2
	v_mov_b32_e32 v46, v2
	v_mov_b32_e32 v47, v2
	v_mov_b32_e32 v48, v2
	v_mov_b32_e32 v49, v2
	v_mov_b32_e32 v18, v2
	v_mov_b32_e32 v19, v2
	v_mov_b32_e32 v20, v2
	v_mov_b32_e32 v21, v2
	v_mov_b32_e32 v22, v2
	v_mov_b32_e32 v23, v2
	v_mov_b32_e32 v24, v2
	v_mov_b32_e32 v25, v2
	v_mov_b32_e32 v34, v2
	v_mov_b32_e32 v35, v2
	v_mov_b32_e32 v36, v2
	v_mov_b32_e32 v37, v2
	v_mov_b32_e32 v38, v2
	v_mov_b32_e32 v39, v2
	v_mov_b32_e32 v40, v2
	v_mov_b32_e32 v41, v2
	v_mov_b32_e32 v50, v2
	v_mov_b32_e32 v51, v2
	v_mov_b32_e32 v52, v2
	v_mov_b32_e32 v53, v2
	v_mov_b32_e32 v54, v2
	v_mov_b32_e32 v55, v2
	v_mov_b32_e32 v56, v2
	v_mov_b32_e32 v57, v2
	v_mov_b32_e32 v58, v2
	v_mov_b32_e32 v59, v2
	v_mov_b32_e32 v60, v2
	v_mov_b32_e32 v61, v2
	v_mov_b32_e32 v62, v2
	v_mov_b32_e32 v63, v2
	v_mov_b32_e32 v64, v2
	v_mov_b32_e32 v65, v2
	v_mov_b32_e32 v66, v2
	v_mov_b32_e32 v67, v2
	v_mov_b32_e32 v68, v2
	v_mov_b32_e32 v69, v2
	v_mov_b32_e32 v70, v2
	v_mov_b32_e32 v71, v2
	v_mov_b32_e32 v72, v2
	v_mov_b32_e32 v73, v2
	v_mov_b32_e32 v74, v2
	v_mov_b32_e32 v75, v2
	v_mov_b32_e32 v76, v2
	v_mov_b32_e32 v77, v2
	v_mov_b32_e32 v78, v2
	v_mov_b32_e32 v79, v2
	v_mov_b32_e32 v80, v2
	v_mov_b32_e32 v81, v2
	v_mov_b32_e32 v90, v2
	v_mov_b32_e32 v91, v2
	v_mov_b32_e32 v92, v2
	v_mov_b32_e32 v93, v2
	v_mov_b32_e32 v94, v2
	v_mov_b32_e32 v95, v2
	v_mov_b32_e32 v96, v2
	v_mov_b32_e32 v97, v2
	v_mov_b32_e32 v106, v2
	v_mov_b32_e32 v107, v2
	v_mov_b32_e32 v108, v2
	v_mov_b32_e32 v109, v2
	v_mov_b32_e32 v110, v2
	v_mov_b32_e32 v111, v2
	v_mov_b32_e32 v112, v2
	v_mov_b32_e32 v113, v2
	v_mov_b32_e32 v82, v2
	v_mov_b32_e32 v83, v2
	v_mov_b32_e32 v84, v2
	v_mov_b32_e32 v85, v2
	v_mov_b32_e32 v86, v2
	v_mov_b32_e32 v87, v2
	v_mov_b32_e32 v88, v2
	v_mov_b32_e32 v89, v2
	v_mov_b32_e32 v98, v2
	v_mov_b32_e32 v99, v2
	v_mov_b32_e32 v100, v2
	v_mov_b32_e32 v101, v2
	v_mov_b32_e32 v102, v2
	v_mov_b32_e32 v103, v2
	v_mov_b32_e32 v104, v2
	v_mov_b32_e32 v105, v2
	v_mov_b32_e32 v114, v2
	v_mov_b32_e32 v115, v2
	v_mov_b32_e32 v116, v2
	v_mov_b32_e32 v117, v2
	v_mov_b32_e32 v118, v2
	v_mov_b32_e32 v119, v2
	v_mov_b32_e32 v120, v2
	v_mov_b32_e32 v121, v2
	v_mov_b32_e32 v122, v2
	v_mov_b32_e32 v123, v2
	v_mov_b32_e32 v124, v2
	v_mov_b32_e32 v125, v2
	v_mov_b32_e32 v126, v2
	v_mov_b32_e32 v127, v2
	v_mov_b32_e32 v128, v2
	v_mov_b32_e32 v129, v2
	.p2align	6

;     __device__ __forceinline__ bool next(int i, Unit& u) const { if (i) return false; u.pm = pm; u.pn = pn; return true; }
; template <class Epi, class Sched, bool ALIGN_EPI = false, bool SP2 = false>
; __device__ __forceinline__ void gemm_phase(PG8_LAS unsigned char* lds, const Gemm g, const Sched& S, const Epi& E) {
;     ...
;         const bool has_next = S.next(ui + 1, nxt);
;         const char* nA = has_next ? (const char*)g.A + (size_t)nxt.pm * tstep : cA; const char* nB = has_next ? (const char*)g.Bt + (size_t)nxt.pn * tstep : cB;
;         for (int t = 0; t < nt; t += 2) {
;             const bool last = (t == nt - 2);
;             const char* a1 = cA + (size_t)(t + 1) * kstep;
;             const char* a2 = last ? nA : cA + (size_t)(t + 2) * kstep; const char* b2 = last ? nB : cB + (size_t)(t + 2) * kstep;
;             const char* a3 = a2 + kstep; const char* b3 = b2 + kstep;
;             if (last && has_next) S.a_ready(nxt);
;     ...
; #pragma unroll
;         for (int a = 0; a < 2; ++a)
; #pragma unroll
;             for (int b = 0; b < 2; ++b)
; #pragma unroll
;                 for (int m = 0; m < 4; ++m)
; #pragma unroll
;                     for (int n = 0; n < 2; ++n) acc[a][b][m][n] = (f32x4){0.f, 0.f, 0.f, 0.f};
;         cur = nxt; cA = nA; cB = nB; ++ui;
.LBB0_703:
	s_ashr_i32 s51, s50, 31
	s_lshl_b64 s[22:23], s[50:51], 20
	s_add_u32 s52, s55, s22
	s_addc_u32 s53, s58, s23
	s_and_b64 s[22:23], s[40:41], exec
	s_cselect_b32 s51, s53, s49
	s_cselect_b32 s84, s52, s48
	s_ashr_i32 s47, s46, 31
	s_lshl_b64 s[22:23], s[46:47], 20
	s_add_u32 s56, s20, s22
	s_addc_u32 s57, s59, s23
	s_and_b64 s[22:23], s[40:41], exec
	s_cselect_b32 s47, s57, s35
	s_cselect_b32 s85, s56, s34
	s_add_u32 s92, s48, 0x80080
	s_addc_u32 s93, s49, 0
	s_add_u32 s86, s34, 0x100
	v_mov_b32_e32 v2, 0
	s_addc_u32 s87, s35, 0
	s_mov_b32 s88, -2
	v_mov_b32_e32 v3, v2
	v_mov_b32_e32 v4, v2
	v_mov_b32_e32 v5, v2
	v_mov_b32_e32 v6, v2
	v_mov_b32_e32 v7, v2
	v_mov_b32_e32 v8, v2
	v_mov_b32_e32 v9, v2
	v_mov_b32_e32 v18, v2
	v_mov_b32_e32 v19, v2
	v_mov_b32_e32 v20, v2
	v_mov_b32_e32 v21, v2
	v_mov_b32_e32 v22, v2
	v_mov_b32_e32 v23, v2
	v_mov_b32_e32 v24, v2
	v_mov_b32_e32 v25, v2
	v_mov_b32_e32 v34, v2
	v_mov_b32_e32 v35, v2
	v_mov_b32_e32 v36, v2
	v_mov_b32_e32 v37, v2
	v_mov_b32_e32 v38, v2
	v_mov_b32_e32 v39, v2
	v_mov_b32_e32 v40, v2
	v_mov_b32_e32 v41, v2
	v_mov_b32_e32 v50, v2
	v_mov_b32_e32 v51, v2
	v_mov_b32_e32 v52, v2
	v_mov_b32_e32 v53, v2
	v_mov_b32_e32 v54, v2
	v_mov_b32_e32 v55, v2
	v_mov_b32_e32 v56, v2
	v_mov_b32_e32 v57, v2
	v_mov_b32_e32 v10, v2
	v_mov_b32_e32 v11, v2
	v_mov_b32_e32 v12, v2
	v_mov_b32_e32 v13, v2
	v_mov_b32_e32 v14, v2
	v_mov_b32_e32 v15, v2
	v_mov_b32_e32 v16, v2
	v_mov_b32_e32 v17, v2
	v_mov_b32_e32 v26, v2
	v_mov_b32_e32 v27, v2
	v_mov_b32_e32 v28, v2
	v_mov_b32_e32 v29, v2
	v_mov_b32_e32 v30, v2
	v_mov_b32_e32 v31, v2
	v_mov_b32_e32 v32, v2
	v_mov_b32_e32 v33, v2
	v_mov_b32_e32 v42, v2
	v_mov_b32_e32 v43, v2
	v_mov_b32_e32 v44, v2
	v_mov_b32_e32 v45, v2
	v_mov_b32_e32 v46, v2
	v_mov_b32_e32 v47, v2
	v_mov_b32_e32 v48, v2
	v_mov_b32_e32 v49, v2
	v_mov_b32_e32 v58, v2
	v_mov_b32_e32 v59, v2
	v_mov_b32_e32 v60, v2
	v_mov_b32_e32 v61, v2
	v_mov_b32_e32 v62, v2
	v_mov_b32_e32 v63, v2
	v_mov_b32_e32 v64, v2
	v_mov_b32_e32 v65, v2
	v_mov_b32_e32 v66, v2
	v_mov_b32_e32 v67, v2
	v_mov_b32_e32 v68, v2
	v_mov_b32_e32 v69, v2
	v_mov_b32_e32 v70, v2
	v_mov_b32_e32 v71, v2
	v_mov_b32_e32 v72, v2
	v_mov_b32_e32 v73, v2
	v_mov_b32_e32 v82, v2
	v_mov_b32_e32 v83, v2
	v_mov_b32_e32 v84, v2
	v_mov_b32_e32 v85, v2
	v_mov_b32_e32 v86, v2
	v_mov_b32_e32 v87, v2
	v_mov_b32_e32 v88, v2
	v_mov_b32_e32 v89, v2
	v_mov_b32_e32 v98, v2
	v_mov_b32_e32 v99, v2
	v_mov_b32_e32 v100, v2
	v_mov_b32_e32 v101, v2
	v_mov_b32_e32 v102, v2
	v_mov_b32_e32 v103, v2
	v_mov_b32_e32 v104, v2
	v_mov_b32_e32 v105, v2
	v_mov_b32_e32 v114, v2
	v_mov_b32_e32 v115, v2
	v_mov_b32_e32 v116, v2
	v_mov_b32_e32 v117, v2
	v_mov_b32_e32 v118, v2
	v_mov_b32_e32 v119, v2
	v_mov_b32_e32 v120, v2
	v_mov_b32_e32 v121, v2
	v_mov_b32_e32 v74, v2
	v_mov_b32_e32 v75, v2
	v_mov_b32_e32 v76, v2
	v_mov_b32_e32 v77, v2
	v_mov_b32_e32 v78, v2
	v_mov_b32_e32 v79, v2
	v_mov_b32_e32 v80, v2
	v_mov_b32_e32 v81, v2
	v_mov_b32_e32 v90, v2
	v_mov_b32_e32 v91, v2
	v_mov_b32_e32 v92, v2
	v_mov_b32_e32 v93, v2
	v_mov_b32_e32 v94, v2
	v_mov_b32_e32 v95, v2
	v_mov_b32_e32 v96, v2
	v_mov_b32_e32 v97, v2
	v_mov_b32_e32 v106, v2
	v_mov_b32_e32 v107, v2
	v_mov_b32_e32 v108, v2
	v_mov_b32_e32 v109, v2
	v_mov_b32_e32 v110, v2
	v_mov_b32_e32 v111, v2
	v_mov_b32_e32 v112, v2
	v_mov_b32_e32 v113, v2
	v_mov_b32_e32 v122, v2
	v_mov_b32_e32 v123, v2
	v_mov_b32_e32 v124, v2
	v_mov_b32_e32 v125, v2
	v_mov_b32_e32 v126, v2
	v_mov_b32_e32 v127, v2
	v_mov_b32_e32 v128, v2
	v_mov_b32_e32 v129, v2
	.p2align	6

; template <class Epi, class Sched, bool ALIGN_EPI = false, bool SP2 = false>
; __device__ __forceinline__ void gemm_phase(PG8_LAS unsigned char* lds, const Gemm g, const Sched& S, const Epi& E) {
;     ...
; #pragma unroll
;         for (int a = 0; a < 2; ++a)
; #pragma unroll
;             for (int b = 0; b < 2; ++b)
; #pragma unroll
;                 for (int m = 0; m < 4; ++m)
; #pragma unroll
;                     for (int n = 0; n < 2; ++n) acc[a][b][m][n] = (f32x4){0.f, 0.f, 0.f, 0.f};
;         cur = nxt; cA = nA; cB = nB; ++ui;
.LBB0_782:
	s_add_u32 s82, s34, 0x100
	v_mov_b32_e32 v2, 0
	s_addc_u32 s83, s35, 0
	s_mov_b32 s84, -2
	v_mov_b32_e32 v3, v2
	v_mov_b32_e32 v4, v2
	v_mov_b32_e32 v5, v2
	v_mov_b32_e32 v6, v2
	v_mov_b32_e32 v7, v2
	v_mov_b32_e32 v8, v2
	v_mov_b32_e32 v9, v2
	v_mov_b32_e32 v10, v2
	v_mov_b32_e32 v11, v2
	v_mov_b32_e32 v12, v2
	v_mov_b32_e32 v13, v2
	v_mov_b32_e32 v14, v2
	v_mov_b32_e32 v15, v2
	v_mov_b32_e32 v16, v2
	v_mov_b32_e32 v17, v2
	v_mov_b32_e32 v26, v2
	v_mov_b32_e32 v27, v2
	v_mov_b32_e32 v28, v2
	v_mov_b32_e32 v29, v2
	v_mov_b32_e32 v30, v2
	v_mov_b32_e32 v31, v2
	v_mov_b32_e32 v32, v2
	v_mov_b32_e32 v33, v2
	v_mov_b32_e32 v42, v2
	v_mov_b32_e32 v43, v2
	v_mov_b32_e32 v44, v2
	v_mov_b32_e32 v45, v2
	v_mov_b32_e32 v46, v2
	v_mov_b32_e32 v47, v2
	v_mov_b32_e32 v48, v2
	v_mov_b32_e32 v49, v2
	v_mov_b32_e32 v18, v2
	v_mov_b32_e32 v19, v2
	v_mov_b32_e32 v20, v2
	v_mov_b32_e32 v21, v2
	v_mov_b32_e32 v22, v2
	v_mov_b32_e32 v23, v2
	v_mov_b32_e32 v24, v2
	v_mov_b32_e32 v25, v2
	v_mov_b32_e32 v34, v2
	v_mov_b32_e32 v35, v2
	v_mov_b32_e32 v36, v2
	v_mov_b32_e32 v37, v2
	v_mov_b32_e32 v38, v2
	v_mov_b32_e32 v39, v2
	v_mov_b32_e32 v40, v2
	v_mov_b32_e32 v41, v2
	v_mov_b32_e32 v50, v2
	v_mov_b32_e32 v51, v2
	v_mov_b32_e32 v52, v2
	v_mov_b32_e32 v53, v2
	v_mov_b32_e32 v54, v2
	v_mov_b32_e32 v55, v2
	v_mov_b32_e32 v56, v2
	v_mov_b32_e32 v57, v2
	v_mov_b32_e32 v58, v2
	v_mov_b32_e32 v59, v2
	v_mov_b32_e32 v60, v2
	v_mov_b32_e32 v61, v2
	v_mov_b32_e32 v62, v2
	v_mov_b32_e32 v63, v2
	v_mov_b32_e32 v64, v2
	v_mov_b32_e32 v65, v2
	v_mov_b32_e32 v66, v2
	v_mov_b32_e32 v67, v2
	v_mov_b32_e32 v68, v2
	v_mov_b32_e32 v69, v2
	v_mov_b32_e32 v70, v2
	v_mov_b32_e32 v71, v2
	v_mov_b32_e32 v72, v2
	v_mov_b32_e32 v73, v2
	v_mov_b32_e32 v74, v2
	v_mov_b32_e32 v75, v2
	v_mov_b32_e32 v76, v2
	v_mov_b32_e32 v77, v2
	v_mov_b32_e32 v78, v2
	v_mov_b32_e32 v79, v2
	v_mov_b32_e32 v80, v2
	v_mov_b32_e32 v81, v2
	v_mov_b32_e32 v90, v2
	v_mov_b32_e32 v91, v2
	v_mov_b32_e32 v92, v2
	v_mov_b32_e32 v93, v2
	v_mov_b32_e32 v94, v2
	v_mov_b32_e32 v95, v2
	v_mov_b32_e32 v96, v2
	v_mov_b32_e32 v97, v2
	v_mov_b32_e32 v106, v2
	v_mov_b32_e32 v107, v2
	v_mov_b32_e32 v108, v2
	v_mov_b32_e32 v109, v2
	v_mov_b32_e32 v110, v2
	v_mov_b32_e32 v111, v2
	v_mov_b32_e32 v112, v2
	v_mov_b32_e32 v113, v2
	v_mov_b32_e32 v82, v2
	v_mov_b32_e32 v83, v2
	v_mov_b32_e32 v84, v2
	v_mov_b32_e32 v85, v2
	v_mov_b32_e32 v86, v2
	v_mov_b32_e32 v87, v2
	v_mov_b32_e32 v88, v2
	v_mov_b32_e32 v89, v2
	v_mov_b32_e32 v98, v2
	v_mov_b32_e32 v99, v2
	v_mov_b32_e32 v100, v2
	v_mov_b32_e32 v101, v2
	v_mov_b32_e32 v102, v2
	v_mov_b32_e32 v103, v2
	v_mov_b32_e32 v104, v2
	v_mov_b32_e32 v105, v2
	v_mov_b32_e32 v114, v2
	v_mov_b32_e32 v115, v2
	v_mov_b32_e32 v116, v2
	v_mov_b32_e32 v117, v2
	v_mov_b32_e32 v118, v2
	v_mov_b32_e32 v119, v2
	v_mov_b32_e32 v120, v2
	v_mov_b32_e32 v121, v2
	v_mov_b32_e32 v122, v2
	v_mov_b32_e32 v123, v2
	v_mov_b32_e32 v124, v2
	v_mov_b32_e32 v125, v2
	v_mov_b32_e32 v126, v2
	v_mov_b32_e32 v127, v2
	v_mov_b32_e32 v128, v2
	v_mov_b32_e32 v129, v2
	.p2align	6
